# P0: the W_up transpose item issues its 8 row loads and 8 g_mlp scale loads together with one wait instead of a load-wait-scale-write ladder per row
# baseline (speedup 1.0000x reference)
; #define LAS __attribute__((address_space(3)))
; __device__ __forceinline__ unsigned cvtpk(float lo, float hi) { return pg8::cvt_pk_bf16(lo, hi); }
;     ...
; #pragma unroll
;     for (int i = 0; i < 8; ++i) { const int kk = 8 * i + (lane >> 3), c4 = lane & 7;
;         f32x4 v = *(const f32x4*)(W + (size_t)(k0 + kk) * N + n0 + 4 * c4) * sscale; if (kscale) v = v * kscale[k0 + kk];
;         LAS float* d = scr + kk * 33 + 4 * c4; d[0] = v[0]; d[1] = v[1]; d[2] = v[2]; d[3] = v[3]; }
;     asm volatile("s_waitcnt lgkmcnt(0)" ::: "memory");
;     const int c = lane & 7;
; #pragma unroll
;     for (int j = 0; j < 4; ++j) { const int n = (lane >> 3) + 8 * j; const LAS float* s = scr + (8 * c) * 33 + n;
;         v4u o; o.x = cvtpk(s[0 * 33], s[1 * 33]); o.y = cvtpk(s[2 * 33], s[3 * 33]); o.z = cvtpk(s[4 * 33], s[5 * 33]); o.w = cvtpk(s[6 * 33], s[7 * 33]);
;         *(v4u*)(WT + (size_t)(n0 + n) * ld + koff + k0 + 8 * c) = o; }
.LBB0_23:
	s_andn2_b64 vcc, exec, s[4:5]
	s_cbranch_vccnz .LBB0_42
	s_add_i32 s0, s49, 0xf280
	s_lshr_b32 s0, s0, 1
	s_and_b32 s44, s0, 0x7fc0
	s_and_b32 s45, s45, 0xfe0
	s_lshl_b32 s28, s45, 2
	v_lshl_add_u64 v[38:39], v[18:19], 0, s[28:29]
	v_or_b32_e32 v156, s44, v40
	v_lshlrev_b32_e32 v12, 14, v156
	v_lshl_add_u64 v[132:133], v[38:39], 0, v[12:13]
	global_load_dwordx4 v[100:103], v[132:133], off
	v_or_b32_e32 v156, s44, v41
	v_lshlrev_b32_e32 v12, 14, v156
	v_lshl_add_u64 v[134:135], v[38:39], 0, v[12:13]
	global_load_dwordx4 v[104:107], v[134:135], off
	v_or_b32_e32 v156, s44, v42
	v_lshlrev_b32_e32 v12, 14, v156
	v_lshl_add_u64 v[136:137], v[38:39], 0, v[12:13]
	global_load_dwordx4 v[108:111], v[136:137], off
	v_or_b32_e32 v156, s44, v43
	v_lshlrev_b32_e32 v12, 14, v156
	v_lshl_add_u64 v[138:139], v[38:39], 0, v[12:13]
	global_load_dwordx4 v[112:115], v[138:139], off
	v_or_b32_e32 v156, s44, v44
	v_lshlrev_b32_e32 v12, 14, v156
	v_lshl_add_u64 v[140:141], v[38:39], 0, v[12:13]
	global_load_dwordx4 v[116:119], v[140:141], off
	v_or_b32_e32 v156, s44, v45
	v_lshlrev_b32_e32 v12, 14, v156
	v_lshl_add_u64 v[142:143], v[38:39], 0, v[12:13]
	global_load_dwordx4 v[120:123], v[142:143], off
	v_or_b32_e32 v156, s44, v46
	v_lshlrev_b32_e32 v12, 14, v156
	v_lshl_add_u64 v[144:145], v[38:39], 0, v[12:13]
	global_load_dwordx4 v[124:127], v[144:145], off
	v_or_b32_e32 v156, s44, v47
	v_lshlrev_b32_e32 v12, 14, v156
	v_lshl_add_u64 v[146:147], v[38:39], 0, v[12:13]
	global_load_dwordx4 v[128:131], v[146:147], off
	v_add_lshl_u32 v64, s44, v40, 2
	s_andn2_b64 vcc, exec, s[14:15]
	s_cbranch_vccnz .Lmy_p0_noscale
	global_load_dword v148, v64, s[12:13] offset:0
	global_load_dword v150, v64, s[12:13] offset:32
	global_load_dword v152, v64, s[12:13] offset:64
	global_load_dword v154, v64, s[12:13] offset:96
	global_load_dword v156, v64, s[12:13] offset:128
	global_load_dword v158, v64, s[12:13] offset:160
	global_load_dword v160, v64, s[12:13] offset:192
	global_load_dword v162, v64, s[12:13] offset:224
	s_waitcnt vmcnt(0)
	v_pk_mul_f32 v[102:103], v[102:103], v[148:149] op_sel_hi:[1,0]
	v_pk_mul_f32 v[100:101], v[100:101], v[148:149] op_sel_hi:[1,0]
	v_pk_mul_f32 v[106:107], v[106:107], v[150:151] op_sel_hi:[1,0]
	v_pk_mul_f32 v[104:105], v[104:105], v[150:151] op_sel_hi:[1,0]
	v_pk_mul_f32 v[110:111], v[110:111], v[152:153] op_sel_hi:[1,0]
	v_pk_mul_f32 v[108:109], v[108:109], v[152:153] op_sel_hi:[1,0]
	v_pk_mul_f32 v[114:115], v[114:115], v[154:155] op_sel_hi:[1,0]
	v_pk_mul_f32 v[112:113], v[112:113], v[154:155] op_sel_hi:[1,0]
	v_pk_mul_f32 v[118:119], v[118:119], v[156:157] op_sel_hi:[1,0]
	v_pk_mul_f32 v[116:117], v[116:117], v[156:157] op_sel_hi:[1,0]
	v_pk_mul_f32 v[122:123], v[122:123], v[158:159] op_sel_hi:[1,0]
	v_pk_mul_f32 v[120:121], v[120:121], v[158:159] op_sel_hi:[1,0]
	v_pk_mul_f32 v[126:127], v[126:127], v[160:161] op_sel_hi:[1,0]
	v_pk_mul_f32 v[124:125], v[124:125], v[160:161] op_sel_hi:[1,0]
	v_pk_mul_f32 v[130:131], v[130:131], v[162:163] op_sel_hi:[1,0]
	v_pk_mul_f32 v[128:129], v[128:129], v[162:163] op_sel_hi:[1,0]
.Lmy_p0_noscale:
	s_waitcnt vmcnt(0)
	ds_write2_b32 v49, v100, v101 offset1:1
	ds_write2_b32 v49, v102, v103 offset0:2 offset1:3
	ds_write2_b32 v50, v104, v105 offset1:1
	ds_write2_b32 v51, v106, v107 offset1:1
	ds_write2_b32 v52, v108, v109 offset1:1
	ds_write2_b32 v53, v110, v111 offset1:1
	ds_write2_b32 v54, v112, v113 offset1:1
	ds_write2_b32 v55, v114, v115 offset1:1
	ds_write2_b32 v56, v116, v117 offset1:1
	ds_write2_b32 v57, v118, v119 offset1:1
	ds_write2_b32 v58, v120, v121 offset1:1
	ds_write2_b32 v59, v122, v123 offset1:1
	ds_write2_b32 v60, v124, v125 offset1:1
	ds_write2_b32 v61, v126, v127 offset1:1
	ds_write2_b32 v62, v128, v129 offset1:1
	ds_write2_b32 v63, v130, v131 offset1:1
	s_waitcnt lgkmcnt(0)
	ds_read2_b32 v[4:5], v48 offset0:33 offset1:41
	ds_read2_b32 v[6:7], v48 offset1:8
	ds_read2_b32 v[8:9], v48 offset0:66 offset1:74
	ds_read2_b32 v[10:11], v48 offset0:99 offset1:107
	ds_read2_b32 v[38:39], v48 offset0:132 offset1:140
	ds_read2_b32 v[64:65], v48 offset0:165 offset1:173
	ds_read2_b32 v[66:67], v48 offset0:198 offset1:206
	ds_read2_b32 v[68:69], v48 offset0:231 offset1:239
	s_and_b32 s0, 0xffff, s45
	s_lshl_b32 s28, s44, 1
	s_waitcnt vmcnt(0) lgkmcnt(6)
	v_cvt_pk_bf16_f32 v0, v6, v4
	v_or_b32_e32 v4, s0, v40
	v_lshl_add_u64 v[70:71], v[20:21], 0, s[28:29]
	v_lshlrev_b32_e32 v12, 11, v4
	s_waitcnt lgkmcnt(4)
	v_cvt_pk_bf16_f32 v1, v8, v10
	s_waitcnt lgkmcnt(2)
	v_cvt_pk_bf16_f32 v2, v38, v64
	s_waitcnt lgkmcnt(0)
	v_cvt_pk_bf16_f32 v3, v66, v68
	v_lshl_add_u64 v[72:73], v[70:71], 0, v[12:13]
	global_store_dwordx4 v[72:73], v[0:3], off
	v_or_b32_e32 v4, s0, v41
	v_lshlrev_b32_e32 v12, 11, v4
	v_cvt_pk_bf16_f32 v0, v7, v5
	v_cvt_pk_bf16_f32 v1, v9, v11
	v_cvt_pk_bf16_f32 v2, v39, v65
	v_cvt_pk_bf16_f32 v3, v67, v69
	ds_read2_b32 v[6:7], v48 offset0:49 offset1:57
	ds_read2_b32 v[8:9], v48 offset0:16 offset1:24
	ds_read2_b32 v[10:11], v48 offset0:82 offset1:90
	ds_read2_b32 v[38:39], v48 offset0:115 offset1:123
	ds_read2_b32 v[64:65], v48 offset0:148 offset1:156
	ds_read2_b32 v[66:67], v48 offset0:181 offset1:189
	ds_read2_b32 v[68:69], v48 offset0:214 offset1:222
	ds_read2_b32 v[72:73], v48 offset0:247 offset1:255
	v_lshl_add_u64 v[4:5], v[70:71], 0, v[12:13]
	global_store_dwordx4 v[4:5], v[0:3], off
	v_or_b32_e32 v4, s0, v42
	v_lshlrev_b32_e32 v12, 11, v4
	s_waitcnt lgkmcnt(6)
	v_cvt_pk_bf16_f32 v0, v8, v6
	s_waitcnt lgkmcnt(4)
	v_cvt_pk_bf16_f32 v1, v10, v38
	s_waitcnt lgkmcnt(2)
	v_cvt_pk_bf16_f32 v2, v64, v66
	s_waitcnt lgkmcnt(0)
	v_cvt_pk_bf16_f32 v3, v68, v72
	v_lshl_add_u64 v[4:5], v[70:71], 0, v[12:13]
	global_store_dwordx4 v[4:5], v[0:3], off
	v_or_b32_e32 v4, s0, v43
	v_lshlrev_b32_e32 v12, 11, v4
	v_cvt_pk_bf16_f32 v0, v9, v7
	v_cvt_pk_bf16_f32 v1, v11, v39
	v_cvt_pk_bf16_f32 v2, v65, v67
	v_cvt_pk_bf16_f32 v3, v69, v73
	v_lshl_add_u64 v[4:5], v[70:71], 0, v[12:13]
	global_store_dwordx4 v[4:5], v[0:3], off
	s_waitcnt lgkmcnt(0)

; #define LAS __attribute__((address_space(3)))
; __device__ __forceinline__ unsigned pk4_fp8(float a, float b, float c, float d) { int r = __builtin_amdgcn_cvt_pk_fp8_f32(a, b, 0, false); r = __builtin_amdgcn_cvt_pk_fp8_f32(c, d, r, true); return (unsigned)r; }
;     ...
;     const int nblk = N / 32, kb = item / nblk, nb = item % nblk, k0 = 64 * kb, n0 = 32 * nb;
; #pragma unroll
;     for (int i = 0; i < 8; ++i) { const int kk = 8 * i + (lane >> 3), c4 = lane & 7;
;         const f32x4 v = *(const f32x4*)(W + (size_t)(k0 + kk) * N + n0 + 4 * c4) * sscale;
;         LAS float* d = scr + kk * 33 + 4 * c4; d[0] = v[0]; d[1] = v[1]; d[2] = v[2]; d[3] = v[3]; }
;     asm volatile("s_waitcnt lgkmcnt(0)" ::: "memory");
;     const int c = lane & 7;
; #pragma unroll
;     for (int j = 0; j < 4; ++j) { const int n = (lane >> 3) + 8 * j; const LAS float* s = scr + (8 * c) * 33 + n;
;         v2u o; o.x = pk4_fp8(s[0 * 33], s[1 * 33], s[2 * 33], s[3 * 33]); o.y = pk4_fp8(s[4 * 33], s[5 * 33], s[6 * 33], s[7 * 33]);
;         *(v2u*)(WT + (size_t)(n0 + n) * ld + koff + k0 + 8 * c) = o; }
;     asm volatile("s_waitcnt lgkmcnt(0)" ::: "memory");
.LBB0_52:
	s_andn2_b64 vcc, exec, s[4:5]
	s_cbranch_vccnz .LBB0_16
	s_mul_hi_i32 s0, s49, 0x66666667
	s_lshr_b32 s1, s0, 31
	s_ashr_i32 s0, s0, 6
	s_add_i32 s0, s0, s1
	s_lshl_b32 s44, s0, 6
	s_mulk_i32 s0, 0xec00
	s_add_i32 s4, s7, s0
	s_ashr_i32 s5, s4, 31
	v_lshl_add_u64 v[38:39], s[4:5], 2, v[34:35]
	v_or_b32_e32 v12, s44, v44
	v_mad_i64_i32 v[68:69], s[0:1], v12, s48, v[38:39]
	v_or_b32_e32 v12, s44, v45
	v_or_b32_e32 v0, s44, v40
	v_or_b32_e32 v2, s44, v41
	v_or_b32_e32 v8, s44, v42
	v_or_b32_e32 v10, s44, v43
	v_mad_i64_i32 v[72:73], s[0:1], v12, s48, v[38:39]
	v_or_b32_e32 v12, s44, v46
	v_or_b32_e32 v80, s44, v47
	v_mad_i64_i32 v[0:1], s[0:1], v0, s48, v[38:39]
	v_mad_i64_i32 v[4:5], s[0:1], v2, s48, v[38:39]
	v_mad_i64_i32 v[8:9], s[0:1], v8, s48, v[38:39]
	v_mad_i64_i32 v[64:65], s[0:1], v10, s48, v[38:39]
	v_mad_i64_i32 v[76:77], s[0:1], v12, s48, v[38:39]
	v_mad_i64_i32 v[38:39], s[0:1], v80, s48, v[38:39]
	global_load_dwordx4 v[0:3], v[0:1], off
	s_nop 0
	global_load_dwordx4 v[4:7], v[4:5], off
	s_nop 0
	global_load_dwordx4 v[8:11], v[8:9], off
	s_nop 0
	global_load_dwordx4 v[64:67], v[64:65], off
	s_nop 0
	global_load_dwordx4 v[68:71], v[68:69], off
	s_nop 0
	global_load_dwordx4 v[72:75], v[72:73], off
	v_mov_b32_e32 v84, v13
	global_load_dwordx4 v[76:79], v[76:77], off
	v_add_u32_e32 v88, s4, v40
	global_load_dwordx4 v[80:83], v[38:39], off
	v_mov_b32_e32 v38, v13
	v_mov_b32_e32 v39, v13
	s_ashr_i32 s45, s44, 31
	v_ashrrev_i32_e32 v89, 31, v88
	v_lshl_add_u64 v[86:87], v[36:37], 0, s[44:45]
	v_lshlrev_b64 v[92:93], 10, v[88:89]
	v_lshl_add_u64 v[92:93], v[86:87], 0, v[92:93]
	v_mov_b32_e32 v85, v13
	v_add_u32_e32 v90, 8, v88
	v_ashrrev_i32_e32 v91, 31, v90
	v_lshlrev_b64 v[90:91], 10, v[90:91]
	s_waitcnt vmcnt(7)
	v_pk_mul_f32 v[0:1], v[0:1], s[8:9] op_sel_hi:[1,0]
	v_pk_mul_f32 v[2:3], v[2:3], s[8:9] op_sel_hi:[1,0]
	s_waitcnt vmcnt(6)
	v_pk_mul_f32 v[6:7], v[6:7], s[8:9] op_sel_hi:[1,0]
	v_pk_mul_f32 v[4:5], v[4:5], s[8:9] op_sel_hi:[1,0]
	s_waitcnt vmcnt(5)
	v_pk_mul_f32 v[10:11], v[10:11], s[8:9] op_sel_hi:[1,0]
	v_pk_mul_f32 v[8:9], v[8:9], s[8:9] op_sel_hi:[1,0]
	s_waitcnt vmcnt(4)
	v_pk_mul_f32 v[66:67], v[66:67], s[8:9] op_sel_hi:[1,0]
	v_pk_mul_f32 v[64:65], v[64:65], s[8:9] op_sel_hi:[1,0]
	s_waitcnt vmcnt(3)
	v_pk_mul_f32 v[70:71], v[70:71], s[8:9] op_sel_hi:[1,0]
	v_pk_mul_f32 v[68:69], v[68:69], s[8:9] op_sel_hi:[1,0]
	s_waitcnt vmcnt(2)
	v_pk_mul_f32 v[74:75], v[74:75], s[8:9] op_sel_hi:[1,0]
	v_pk_mul_f32 v[72:73], v[72:73], s[8:9] op_sel_hi:[1,0]
	s_waitcnt vmcnt(1)
	v_pk_mul_f32 v[78:79], v[78:79], s[8:9] op_sel_hi:[1,0]
	v_pk_mul_f32 v[76:77], v[76:77], s[8:9] op_sel_hi:[1,0]
	s_waitcnt vmcnt(0)
	v_pk_mul_f32 v[82:83], v[82:83], s[8:9] op_sel_hi:[1,0]
	v_pk_mul_f32 v[80:81], v[80:81], s[8:9] op_sel_hi:[1,0]
	ds_write2_b32 v49, v0, v1 offset1:1
	ds_write2_b32 v49, v2, v3 offset0:2 offset1:3
	ds_write2_b32 v50, v4, v5 offset1:1
	ds_write2_b32 v51, v6, v7 offset1:1
	ds_write2_b32 v52, v8, v9 offset1:1
	ds_write2_b32 v53, v10, v11 offset1:1
	ds_write2_b32 v54, v64, v65 offset1:1
	ds_write2_b32 v55, v66, v67 offset1:1
	ds_write2_b32 v56, v68, v69 offset1:1
	ds_write2_b32 v57, v70, v71 offset1:1
	ds_write2_b32 v58, v72, v73 offset1:1
	ds_write2_b32 v59, v74, v75 offset1:1
	ds_write2_b32 v60, v76, v77 offset1:1
	ds_write2_b32 v61, v78, v79 offset1:1
	ds_write2_b32 v62, v80, v81 offset1:1
	ds_write2_b32 v63, v82, v83 offset1:1
	s_waitcnt lgkmcnt(0)
	ds_read2_b32 v[0:1], v48 offset0:33 offset1:41
	ds_read2_b32 v[2:3], v48 offset0:66 offset1:74
	ds_read2_b32 v[4:5], v48 offset1:8
	ds_read2_b32 v[6:7], v48 offset0:132 offset1:140
	ds_read2_b32 v[8:9], v48 offset0:165 offset1:173
	ds_read2_b32 v[10:11], v48 offset0:99 offset1:107
	ds_read2_b32 v[64:65], v48 offset0:198 offset1:206
	ds_read2_b32 v[66:67], v48 offset0:231 offset1:239
	s_waitcnt lgkmcnt(5)
	v_cvt_pk_fp8_f32 v38, v4, v0
	s_waitcnt lgkmcnt(3)
	v_cvt_pk_fp8_f32 v39, v6, v8
	v_cvt_pk_fp8_f32 v84, v5, v1
	ds_read2_b32 v[0:1], v48 offset0:49 offset1:57
	s_waitcnt lgkmcnt(3)
	v_cvt_pk_fp8_f32 v38, v2, v10 op_sel:[0,0,1]
	s_waitcnt lgkmcnt(1)
	v_cvt_pk_fp8_f32 v39, v64, v66 op_sel:[0,0,1]
	v_cvt_pk_fp8_f32 v85, v7, v9
	v_cvt_pk_fp8_f32 v84, v3, v11 op_sel:[0,0,1]
	v_mov_b32_e32 v8, v13
	global_store_dwordx2 v[92:93], v[38:39], off
	ds_read2_b32 v[2:3], v48 offset0:82 offset1:90
	ds_read2_b32 v[4:5], v48 offset0:16 offset1:24
	ds_read2_b32 v[6:7], v48 offset0:115 offset1:123
	ds_read2_b32 v[10:11], v48 offset0:148 offset1:156
	ds_read2_b32 v[38:39], v48 offset0:181 offset1:189
	v_cvt_pk_fp8_f32 v85, v65, v67 op_sel:[0,0,1]
	ds_read2_b32 v[64:65], v48 offset0:214 offset1:222
	ds_read2_b32 v[66:67], v48 offset0:247 offset1:255
	s_waitcnt lgkmcnt(5)
	v_cvt_pk_fp8_f32 v8, v4, v0
	v_mov_b32_e32 v0, v13
	v_mov_b32_e32 v9, v13
	v_cvt_pk_fp8_f32 v0, v5, v1
	v_mov_b32_e32 v1, v13
	s_waitcnt lgkmcnt(2)
	v_cvt_pk_fp8_f32 v9, v10, v38
	v_cvt_pk_fp8_f32 v1, v11, v39
	v_lshl_add_u64 v[68:69], v[86:87], 0, v[90:91]
	global_store_dwordx2 v[68:69], v[84:85], off
	v_cvt_pk_fp8_f32 v8, v2, v6 op_sel:[0,0,1]
	s_waitcnt lgkmcnt(0)
	v_cvt_pk_fp8_f32 v9, v64, v66 op_sel:[0,0,1]
	v_add_u32_e32 v68, 16, v88
	v_cvt_pk_fp8_f32 v0, v3, v7 op_sel:[0,0,1]
	v_cvt_pk_fp8_f32 v1, v65, v67 op_sel:[0,0,1]
	v_add_u32_e32 v2, 24, v88
	v_ashrrev_i32_e32 v69, 31, v68
	v_ashrrev_i32_e32 v3, 31, v2
	v_lshlrev_b64 v[68:69], 10, v[68:69]
	v_lshlrev_b64 v[2:3], 10, v[2:3]
	v_lshl_add_u64 v[4:5], v[86:87], 0, v[68:69]
	v_lshl_add_u64 v[2:3], v[86:87], 0, v[2:3]
	global_store_dwordx2 v[4:5], v[8:9], off
	global_store_dwordx2 v[2:3], v[0:1], off
	s_waitcnt lgkmcnt(0)
	s_branch .LBB0_16
; __global__ void __launch_bounds__(512, 2) mk_fwd(Args a) {
;     ...
;         f32x4 gv[4];
; #pragma unroll
;         for (int j = 0; j < 4; ++j) gv[j] = ((const f32x4*)g_mix)[lane + 64 * j];
;         for (int m = gw; m < TT; m += 2 * NGW) {
;             const int m2 = m + NGW; const bool has2 = m2 < TT;
;             const float* xrow = (m < TP) ? x_p + (size_t)m * DM : x_s + (size_t)(m - TP) * DM;
;             const float* xrow2 = has2 ? ((m2 < TP) ? x_p + (size_t)m2 * DM : x_s + (size_t)(m2 - TP) * DM) : xrow;
;             const f32x4* xr = (const f32x4*)xrow + lane; const f32x4* xr2 = (const f32x4*)xrow2 + lane; f32x4 v[4], w2[4]; float s2 = 0.f, t2 = 0.f;
; #pragma unroll
;             for (int j = 0; j < 4; ++j) { v[j] = xr[64 * j]; w2[j] = xr2[64 * j]; }
; #pragma unroll
;             for (int j = 0; j < 4; ++j) { s2 += (v[j].x * v[j].x + v[j].y * v[j].y) + (v[j].z * v[j].z + v[j].w * v[j].w); t2 += (w2[j].x * w2[j].x + w2[j].y * w2[j].y) + (w2[j].z * w2[j].z + w2[j].w * w2[j].w); }
;             const float rs = __builtin_amdgcn_rsqf(wave_sum(s2) * (1.f / DM) + RMS_EPS), rt = __builtin_amdgcn_rsqf(wave_sum(t2) * (1.f / DM) + RMS_EPS);
.LBB0_55:
	s_add_u32 s16, s22, 0x3000000
	s_addc_u32 s17, s23, 0
	s_cmp_lt_i32 s6, 0x14000
	s_cbranch_scc0 .LBB0_65
	v_and_b32_e32 v20, 63, v254
	v_lshlrev_b32_e32 v16, 4, v20
	global_load_dwordx4 v[0:3], v16, s[42:43]
	global_load_dwordx4 v[4:7], v16, s[42:43] offset:1024
	global_load_dwordx4 v[8:11], v16, s[42:43] offset:2048
	global_load_dwordx4 v[12:15], v16, s[42:43] offset:3072
	v_mov_b32_e32 v17, 0
	v_lshlrev_b32_e32 v16, 2, v20
	v_lshl_add_u64 v[32:33], s[16:17], 0, v[16:17]
	v_mbcnt_lo_u32_b32 v16, -1, 0
	v_mbcnt_hi_u32_b32 v16, -1, v16
	v_and_b32_e32 v17, 64, v16
	v_add_u32_e32 v17, 64, v17
	v_xor_b32_e32 v18, 1, v16
	v_cmp_lt_i32_e32 vcc, v18, v17
	s_mov_b32 s5, 0
	v_lshlrev_b32_e32 v40, 4, v20
	v_cndmask_b32_e32 v18, v16, v18, vcc
	v_lshlrev_b32_e32 v34, 2, v18
	v_xor_b32_e32 v18, 2, v16
	v_cmp_lt_i32_e32 vcc, v18, v17
	v_mov_b32_e32 v41, 0x358637bd
	s_nop 0
	v_cndmask_b32_e32 v18, v16, v18, vcc
	v_lshlrev_b32_e32 v35, 2, v18
	v_xor_b32_e32 v18, 4, v16
	v_cmp_lt_i32_e32 vcc, v18, v17
	s_nop 1
	v_cndmask_b32_e32 v18, v16, v18, vcc
	v_lshlrev_b32_e32 v36, 2, v18
	v_xor_b32_e32 v18, 8, v16
	v_cmp_lt_i32_e32 vcc, v18, v17
	s_nop 1
	v_cndmask_b32_e32 v18, v16, v18, vcc
	v_lshlrev_b32_e32 v37, 2, v18
	v_xor_b32_e32 v18, 16, v16
	v_cmp_lt_i32_e32 vcc, v18, v17
	s_nop 1
	v_cndmask_b32_e32 v18, v16, v18, vcc
	v_lshlrev_b32_e32 v38, 2, v18
	v_xor_b32_e32 v18, 32, v16
	v_cmp_lt_i32_e32 vcc, v18, v17
	s_nop 1
	v_cndmask_b32_e32 v16, v16, v18, vcc
	v_lshlrev_b32_e32 v39, 2, v16
	s_branch .LBB0_58
